# v41 + FFN-up epilogue conv weights/bias prefetched by LDS-DMA at tile start (ds_read in epilogue, no vmcnt(0) drain)
# speedup vs baseline: 1.0006x; 1.0006x over previous
; #define LAS __attribute__((address_space(3)))
; __device__ __forceinline__ int opaque_tid() { int t = threadIdx.x; asm volatile("" : "+v"(t)); return t; }
;     __device__ __forceinline__ void prefetch(const Unit& u, int ui) const { if (rs) rs_prefetch(rs, u.pm, ui); }
;     __device__ __forceinline__ void prefetch(const Unit& u, int ui) const { rs_prefetch(rs, u.pm, ui); }
; __device__ __forceinline__ void rs_prefetch(const float* rs, int pm, int ui) {
;     const int t = opaque_tid(), w = __builtin_amdgcn_readfirstlane(t >> 6);
;     extern __shared__ __attribute__((aligned(16))) unsigned char lds_dyn_[];
;     if (w < 4) __builtin_amdgcn_global_load_lds((const unsigned*)(rs + pm * BM + t), (LAS unsigned*)((LAS unsigned char*)lds_dyn_ + L_RSPF + (ui & 1) * 1024 + w * 256), 4, 0, 0);
; }
;     __device__ __forceinline__ void prefetch(const Unit& u, int ui) const { rs_prefetch(rs, u.pm, ui); }
.LBB0_1521:
	v_mov_b32_e32 v4, v0
	s_nop 0
	v_readfirstlane_b32 s14, v4
	s_ashr_i32 s14, s14, 6
	v_and_b32_e32 v6, 63, v4
	s_lshr_b32 s40, s14, 1
	s_and_b32 s41, s14, 1
	s_lshl_b32 s41, s41, 6
	s_lshl_b32 s15, s53, 7
	s_add_i32 s15, s15, s41
	v_add_lshl_u32 v6, v6, s15, 2
	s_cmp_lt_u32 s40, 2
	s_cselect_b32 vcc_lo, s36, s50
	s_cselect_b32 vcc_hi, s37, s51
	s_cmp_eq_u32 s40, 1
	s_cselect_b32 vcc_lo, s48, vcc_lo
	s_cselect_b32 vcc_hi, s49, vcc_hi
	s_cmp_eq_u32 s40, 3
	s_cselect_b32 vcc_lo, s42, vcc_lo
	s_cselect_b32 vcc_hi, s43, vcc_hi
	s_and_b32 s41, s66, 1
	s_lshl_b32 s41, s41, 11
	s_lshl_b32 s15, s14, 8
	s_add_i32 s41, s41, s15
	s_add_i32 m0, s41, 0x22000
	s_nop 0
	global_load_lds_dword v6, vcc
	s_cmp_gt_i32 s14, 3
	s_cbranch_scc1 .LBB0_1523
	s_lshl_b32 s40, s52, 8
	s_ashr_i32 s41, s40, 31
	s_lshl_b64 s[40:41], s[40:41], 2
	v_readlane_b32 s58, v252, 14
	v_readlane_b32 s59, v252, 15
	s_add_u32 s40, s58, s40
	s_addc_u32 s41, s59, s41
	s_lshl_b32 s15, s66, 10
	s_and_b32 s15, s15, 0x400
	s_add_i32 s15, s15, 0
	s_lshl_b32 s14, s14, 8
	v_ashrrev_i32_e32 v5, 31, v4
	s_add_i32 s14, s15, s14
	v_lshl_add_u64 v[4:5], v[4:5], 2, s[40:41]
	s_add_i32 m0, s14, 0x21000
	s_nop 0
	global_load_lds_dword v[4:5], off

; #define LAS __attribute__((address_space(3)))
; __device__ __forceinline__ int opaque_tid() { int t = threadIdx.x; asm volatile("" : "+v"(t)); return t; }
;     __device__ __forceinline__ void operator()(f32x4 (&acc)[2][2][4][2], const Unit& u, int wr, int wc, int ui, int) const {
;         const int ol_ = opaque_tid() & 63, fr = ol_ & 15, fq = ol_ >> 4;
;         { float r_[2][4];
;           rs_read(r_, ui, wr, fr);
; #pragma unroll
;           for (int ai = 0; ai < 2; ++ai)
; #pragma unroll
;               for (int bj = 0; bj < 2; ++bj)
; #pragma unroll
;                   for (int m = 0; m < 4; ++m) { acc[ai][bj][m][0] *= r_[ai][m]; acc[ai][bj][m][1] *= r_[ai][m]; } }
;         const int col = u.pn * 128 + wc * 32 + 8 * fq;
;         if (fr >= 14) {
; #pragma unroll
;             for (int ai = 0; ai < 2; ++ai) { LAS f32x4* s = (LAS f32x4*)(hl + ((((ai * 2 + wr) * 4 + wc) * 8 + fq * 2 + (fr - 14)) * 32));
;                 s[0] = acc[ai][1][3][0]; s[1] = acc[ai][1][3][1]; }
;         }
;         asm volatile("s_waitcnt lgkmcnt(0)" ::: "memory"); __builtin_amdgcn_s_barrier(); asm volatile("" ::: "memory");
;         __builtin_amdgcn_s_barrier(); asm volatile("" ::: "memory");
;         float w0[8], w1[8], w2[8], bb[8];
;         { const f32x4 a0 = *(const f32x4*)(cw + col), a1 = *(const f32x4*)(cw + col + 4), b0 = *(const f32x4*)(cw + FF + col), b1 = *(const f32x4*)(cw + FF + col + 4),
;                       c0 = *(const f32x4*)(cw + 2 * FF + col), c1 = *(const f32x4*)(cw + 2 * FF + col + 4), d0 = *(const f32x4*)(cb + col), d1 = *(const f32x4*)(cb + col + 4);
.Lalign_a_1526:
	v_bfe_u32 v186, v0, 4, 2
	s_lshl_b32 s4, s53, 7
	s_or_b32 s4, s4, s29
	v_lshl_or_b32 v186, v186, 3, s4
	v_lshlrev_b32_e32 v186, 2, v186
	s_and_b32 s5, s66, 1
	s_lshl_b32 s5, s5, 11
	s_lshl_b32 s4, s53, 9
	s_sub_i32 s5, s5, s4
	s_add_i32 s5, s5, 0x22000
	v_add_u32_e32 v134, s5, v186
	ds_read_b128 v[162:165], v134 offset:16
	ds_read_b128 v[170:173], v134
	ds_read_b128 v[154:157], v134 offset:528
	ds_read_b128 v[166:169], v134 offset:512
	ds_read_b128 v[146:149], v134 offset:1040
	ds_read_b128 v[158:161], v134 offset:1024
	ds_read_b128 v[142:145], v134 offset:1552
	ds_read_b128 v[150:153], v134 offset:1536
	s_lshl_b32 s4, s66, 10
	v_mov_b32_e32 v134, v0
	s_and_b32 s4, s4, 0x400
	s_add_i32 s4, s35, s4
	v_and_b32_e32 v210, 15, v134
	v_lshl_add_u32 v2, v210, 2, s4
	ds_read2_b32 v[204:205], v2 offset1:16
	ds_read2_b32 v[202:203], v2 offset0:32 offset1:48
	ds_read2_b32 v[198:199], v2 offset0:128 offset1:144
	ds_read2_b32 v[196:197], v2 offset0:160 offset1:176
	v_cmp_lt_u32_e32 vcc, 13, v210
	s_waitcnt lgkmcnt(0)
	v_mov_b32_e32 v206, v205
	v_mov_b32_e32 v208, v203
	v_mov_b32_e32 v2, v199
	v_mov_b32_e32 v200, v197
	v_pk_mul_f32 v[132:133], v[130:131], v[208:209] op_sel_hi:[1,0]
	v_pk_mul_f32 v[130:131], v[128:129], v[208:209] op_sel_hi:[1,0]
	v_pk_mul_f32 v[128:129], v[126:127], v[208:209] op_sel_hi:[1,0]
	v_pk_mul_f32 v[126:127], v[124:125], v[208:209] op_sel_hi:[1,0]
	v_pk_mul_f32 v[62:63], v[62:63], v[200:201] op_sel_hi:[1,0]
	v_pk_mul_f32 v[60:61], v[60:61], v[200:201] op_sel_hi:[1,0]
	v_pk_mul_f32 v[66:67], v[66:67], v[200:201] op_sel_hi:[1,0]
	v_pk_mul_f32 v[64:65], v[64:65], v[200:201] op_sel_hi:[1,0]
	v_bfe_u32 v125, v134, 4, 2
	s_and_saveexec_b64 s[4:5], vcc
	s_cbranch_execz .LBB0_1529
	v_lshlrev_b32_e32 v124, 1, v125
	v_add3_u32 v124, v210, v124, -14
	v_add_u32_e32 v134, s39, v124
	v_add_u32_e32 v124, s38, v124
	v_lshl_add_u32 v124, v124, 5, s62
	v_lshl_add_u32 v134, v134, 5, s62
	ds_write_b128 v124, v[130:133]
	ds_write_b128 v124, v[126:129] offset:16
	ds_write_b128 v134, v[60:63]
	ds_write_b128 v134, v[64:67] offset:16

; #define LAS __attribute__((address_space(3)))
;     __device__ __forceinline__ void operator()(f32x4 (&acc)[2][2][4][2], const Unit& u, int wr, int wc, int ui, int) const {
;     ...
;         { const f32x4 a0 = *(const f32x4*)(cw + col), a1 = *(const f32x4*)(cw + col + 4), b0 = *(const f32x4*)(cw + FF + col), b1 = *(const f32x4*)(cw + FF + col + 4),
;                       c0 = *(const f32x4*)(cw + 2 * FF + col), c1 = *(const f32x4*)(cw + 2 * FF + col + 4), d0 = *(const f32x4*)(cb + col), d1 = *(const f32x4*)(cb + col + 4);
; #pragma unroll
;           for (int e = 0; e < 4; ++e) { w0[e] = a0[e] * -LOG2E; w0[4 + e] = a1[e] * -LOG2E; w1[e] = b0[e] * -LOG2E; w1[4 + e] = b1[e] * -LOG2E; w2[e] = c0[e] * -LOG2E; w2[4 + e] = c1[e] * -LOG2E; bb[e] = d0[e] * -LOG2E; bb[4 + e] = d1[e] * -LOG2E; } }
; #pragma unroll
;         for (int ai = 0; ai < 2; ++ai) {
;             f32x4 hal[2] = {(f32x4){0.f, 0.f, 0.f, 0.f}, (f32x4){0.f, 0.f, 0.f, 0.f}};
;             if (!(ai == 0 && wr == 0) && fr >= 14) {
;                 const int sai = (wr == 1) ? ai : 0, swr = (wr == 1) ? 0 : 1;
;                 const LAS f32x4* s = (const LAS f32x4*)(hl + ((((sai * 2 + swr) * 4 + wc) * 8 + fq * 2 + (fr - 14)) * 32));
;                 hal[0] = s[0]; hal[1] = s[1];
;             }
; #pragma unroll
;             for (int m = 0; m < 4; ++m) {
;                 const int row = u.pm * BM + ai * HALF + wr * 64 + m * 16 + fr;
;                 float o[8], z[8], g1[8], g2[8];
; #pragma unroll
;                 for (int k = 0; k < 8; ++k) { const int n = k >> 2, e = k & 3;
;                     const float gc = acc[ai][1][m][n][e], gp = (m == 0) ? hal[n][e] : acc[ai][1][m - 1][n][e];
;                     const int gci = __builtin_bit_cast(int, gc), gpi = __builtin_bit_cast(int, gp);
;                     const int r1 = __builtin_amdgcn_update_dpp(0, gpi, 0x121, 0xf, 0xf, true), r2 = __builtin_amdgcn_update_dpp(0, gpi, 0x122, 0xf, 0xf, true);
;                     g1[k] = __builtin_bit_cast(float, __builtin_amdgcn_update_dpp(r1, gci, 0x111, 0xf, 0xf, false));
;                     g2[k] = __builtin_bit_cast(float, __builtin_amdgcn_update_dpp(r2, gci, 0x112, 0xf, 0xf, false)); }
; #pragma unroll
;                 for (int k = 0; k < 8; ++k) z[k] = w0[k] * g2[k] + bb[k];
; #pragma unroll
;                 for (int k = 0; k < 8; ++k) z[k] += w1[k] * g1[k];
; #pragma unroll
.LBB0_1531:
	s_or_b64 exec, exec, s[4:5]
	s_mov_b32 s4, 0xbfb8aa3b
	v_pk_mul_f32 v[192:193], v[158:159], s[4:5] op_sel_hi:[1,0]
	v_pk_mul_f32 v[158:159], v[146:147], s[4:5] op_sel_hi:[1,0]
	v_pk_mul_f32 v[194:195], v[150:151], s[4:5] op_sel_hi:[1,0]
	v_pk_mul_f32 v[150:151], v[142:143], s[4:5] op_sel_hi:[1,0]
	v_pk_mul_f32 v[142:143], v[164:165], s[4:5] op_sel_hi:[1,0]
	v_pk_mul_f32 v[164:165], v[168:169], s[4:5] op_sel_hi:[1,0]
	v_pk_mul_f32 v[146:147], v[156:157], s[4:5] op_sel_hi:[1,0]
	v_pk_mul_f32 v[156:157], v[160:161], s[4:5] op_sel_hi:[1,0]
	v_pk_mul_f32 v[160:161], v[122:123], v[206:207] op_sel_hi:[1,0]
	v_pk_mul_f32 v[168:169], v[120:121], v[206:207] op_sel_hi:[1,0]
	v_pk_mul_f32 v[120:121], v[116:117], v[206:207] op_sel_hi:[1,0]
	v_mov_b32_e32 v116, v208
	v_mov_b32_e32 v117, v208
	v_pk_mul_f32 v[76:77], v[76:77], v[204:205] op_sel_hi:[1,0]
	v_pk_mul_f32 v[122:123], v[96:97], v[206:207] op_sel_hi:[1,0]
	v_pk_mul_f32 v[96:97], v[94:95], v[206:207] op_sel_hi:[1,0]
	s_waitcnt lgkmcnt(1)
	v_mov_b32_dpp v94, v138 row_ror:2 row_mask:0xf bank_mask:0xf bound_ctrl:1
	v_mov_b32_dpp v95, v139 row_ror:2 row_mask:0xf bank_mask:0xf bound_ctrl:1
	v_pk_mul_f32 v[170:171], v[170:171], s[4:5] op_sel_hi:[1,0]
	v_pk_mul_f32 v[106:107], v[106:107], v[116:117]
	v_pk_mul_f32 v[102:103], v[102:103], v[116:117]
	v_pk_mul_f32 v[116:117], v[98:99], v[206:207] op_sel_hi:[1,0]
	v_pk_mul_f32 v[98:99], v[92:93], v[206:207] op_sel_hi:[1,0]
	v_pk_mul_f32 v[92:93], v[88:89], v[202:203] op_sel_hi:[1,0]
	v_mov_b32_dpp v88, v138 row_ror:1 row_mask:0xf bank_mask:0xf bound_ctrl:1
	v_mov_b32_dpp v94, v76 row_shr:2 row_mask:0xf bank_mask:0xf
	v_mov_b32_dpp v89, v139 row_ror:1 row_mask:0xf bank_mask:0xf bound_ctrl:1
	v_mov_b32_dpp v95, v77 row_shr:2 row_mask:0xf bank_mask:0xf
	v_pk_mul_f32 v[190:191], v[166:167], s[4:5] op_sel_hi:[1,0]
	v_mov_b32_dpp v88, v76 row_shr:1 row_mask:0xf bank_mask:0xf
	v_mov_b32_dpp v89, v77 row_shr:1 row_mask:0xf bank_mask:0xf
	v_pk_fma_f32 v[94:95], v[170:171], v[94:95], v[194:195]
	v_pk_mul_f32 v[78:79], v[78:79], v[204:205] op_sel_hi:[1,0]
	v_pk_fma_f32 v[88:89], v[190:191], v[88:89], v[94:95]
	v_mov_b32_dpp v138, v140 row_ror:1 row_mask:0xf bank_mask:0xf bound_ctrl:1
	v_pk_fma_f32 v[88:89], v[76:77], v[192:193], v[88:89]
	v_mov_b32_dpp v140, v140 row_ror:2 row_mask:0xf bank_mask:0xf bound_ctrl:1
	v_mov_b32_dpp v139, v141 row_ror:1 row_mask:0xf bank_mask:0xf bound_ctrl:1
	v_mov_b32_dpp v141, v141 row_ror:2 row_mask:0xf bank_mask:0xf bound_ctrl:1
	v_exp_f32_e32 v94, v88
	v_exp_f32_e32 v95, v89
	v_pk_mul_f32 v[166:167], v[172:173], s[4:5] op_sel_hi:[1,0]
	v_pk_mul_f32 v[152:153], v[152:153], s[4:5] op_sel_hi:[1,0]
	v_mov_b32_dpp v140, v78 row_shr:2 row_mask:0xf bank_mask:0xf
	v_mov_b32_dpp v141, v79 row_shr:2 row_mask:0xf bank_mask:0xf
	v_mov_b32_dpp v138, v78 row_shr:1 row_mask:0xf bank_mask:0xf
	v_mov_b32_dpp v139, v79 row_shr:1 row_mask:0xf bank_mask:0xf
	v_pk_fma_f32 v[140:141], v[166:167], v[140:141], v[152:153]
	v_add_f32_e32 v94, 1.0, v94
	v_pk_fma_f32 v[138:139], v[164:165], v[138:139], v[140:141]
	v_add_f32_e32 v95, 1.0, v95
	v_pk_fma_f32 v[138:139], v[78:79], v[156:157], v[138:139]
	v_pk_mul_f32 v[114:115], v[114:115], v[202:203] op_sel_hi:[1,0]
	v_pk_mul_f32 v[112:113], v[112:113], v[202:203] op_sel_hi:[1,0]
	v_pk_mul_f32 v[110:111], v[110:111], v[202:203] op_sel_hi:[1,0]
	v_pk_mul_f32 v[108:109], v[108:109], v[202:203] op_sel_hi:[1,0]
	v_pk_mul_f32 v[80:81], v[80:81], v[204:205] op_sel_hi:[1,0]
	v_pk_mul_f32 v[90:91], v[90:91], v[202:203] op_sel_hi:[1,0]
	v_pk_mul_f32 v[86:87], v[86:87], v[202:203] op_sel_hi:[1,0]
	v_pk_mul_f32 v[84:85], v[84:85], v[202:203] op_sel_hi:[1,0]
	s_waitcnt lgkmcnt(0)
	v_mov_b32_dpp v202, v134 row_ror:1 row_mask:0xf bank_mask:0xf bound_ctrl:1
	v_mov_b32_dpp v134, v134 row_ror:2 row_mask:0xf bank_mask:0xf bound_ctrl:1
	v_mov_b32_dpp v203, v135 row_ror:1 row_mask:0xf bank_mask:0xf bound_ctrl:1
	v_mov_b32_dpp v135, v135 row_ror:2 row_mask:0xf bank_mask:0xf bound_ctrl:1
	v_rcp_f32_e32 v94, v94
	v_rcp_f32_e32 v95, v95
	v_exp_f32_e32 v125, v138
	v_exp_f32_e32 v140, v139
	v_pk_mul_f32 v[162:163], v[162:163], s[4:5] op_sel_hi:[1,0]
	v_mov_b32_dpp v134, v80 row_shr:2 row_mask:0xf bank_mask:0xf
	v_mov_b32_dpp v135, v81 row_shr:2 row_mask:0xf bank_mask:0xf
	v_pk_mul_f32 v[154:155], v[154:155], s[4:5] op_sel_hi:[1,0]
	v_pk_mul_f32 v[68:69], v[68:69], v[204:205] op_sel_hi:[1,0]
	v_mov_b32_dpp v202, v80 row_shr:1 row_mask:0xf bank_mask:0xf
	v_mov_b32_dpp v203, v81 row_shr:1 row_mask:0xf bank_mask:0xf
	v_pk_fma_f32 v[134:135], v[162:163], v[134:135], v[150:151]
	v_pk_mul_f32 v[88:89], v[68:69], v[88:89]
	v_pk_fma_f32 v[134:135], v[154:155], v[202:203], v[134:135]
	v_pk_mul_f32 v[70:71], v[70:71], v[204:205] op_sel_hi:[1,0]
	v_pk_mul_f32 v[74:75], v[74:75], v[204:205] op_sel_hi:[1,0]
	v_pk_mul_f32 v[72:73], v[72:73], v[204:205] op_sel_hi:[1,0]
	v_pk_mul_f32 v[82:83], v[82:83], v[204:205] op_sel_hi:[1,0]
	v_mov_b32_dpp v204, v136 row_ror:1 row_mask:0xf bank_mask:0xf bound_ctrl:1
	v_mov_b32_dpp v136, v136 row_ror:2 row_mask:0xf bank_mask:0xf bound_ctrl:1
	v_mov_b32_dpp v205, v137 row_ror:1 row_mask:0xf bank_mask:0xf bound_ctrl:1
	v_mov_b32_dpp v137, v137 row_ror:2 row_mask:0xf bank_mask:0xf bound_ctrl:1
	v_pk_mul_f32 v[88:89], v[88:89], v[94:95]
	v_add_f32_e32 v94, 1.0, v125
	v_add_f32_e32 v95, 1.0, v140
	v_pk_fma_f32 v[134:135], v[80:81], v[158:159], v[134:135]
	v_pk_mul_f32 v[144:145], v[144:145], s[4:5] op_sel_hi:[1,0]
	v_mov_b32_dpp v136, v82 row_shr:2 row_mask:0xf bank_mask:0xf
	v_mov_b32_dpp v137, v83 row_shr:2 row_mask:0xf bank_mask:0xf
	v_rcp_f32_e32 v94, v94
	v_rcp_f32_e32 v95, v95
	v_exp_f32_e32 v140, v135
; __device__ __forceinline__ unsigned cvt_pk_bf16(float lo, float hi) { const f32x2 v = {lo, hi}; const bf16v2_ r = __builtin_convertvector(v, bf16v2_); return __builtin_bit_cast(unsigned, r); }
;     __device__ __forceinline__ void operator()(f32x4 (&acc)[2][2][4][2], const Unit& u, int wr, int wc, int ui, int) const {
;     ...
;             for (int m = 0; m < 4; ++m) {
;                 const int row = u.pm * BM + ai * HALF + wr * 64 + m * 16 + fr;
;                 float o[8], z[8], g1[8], g2[8];
; #pragma unroll
;                 for (int k = 0; k < 8; ++k) { const int n = k >> 2, e = k & 3;
;                     const float gc = acc[ai][1][m][n][e], gp = (m == 0) ? hal[n][e] : acc[ai][1][m - 1][n][e];
;                     const int gci = __builtin_bit_cast(int, gc), gpi = __builtin_bit_cast(int, gp);
;                     const int r1 = __builtin_amdgcn_update_dpp(0, gpi, 0x121, 0xf, 0xf, true), r2 = __builtin_amdgcn_update_dpp(0, gpi, 0x122, 0xf, 0xf, true);
;                     g1[k] = __builtin_bit_cast(float, __builtin_amdgcn_update_dpp(r1, gci, 0x111, 0xf, 0xf, false));
;                     g2[k] = __builtin_bit_cast(float, __builtin_amdgcn_update_dpp(r2, gci, 0x112, 0xf, 0xf, false)); }
; #pragma unroll
;                 for (int k = 0; k < 8; ++k) z[k] = w0[k] * g2[k] + bb[k];
; #pragma unroll
;                 for (int k = 0; k < 8; ++k) z[k] += w1[k] * g1[k];
; #pragma unroll
;                 for (int k = 0; k < 8; ++k) z[k] += w2[k] * acc[ai][1][m][k >> 2][k & 3];
; #pragma unroll
;                 for (int k = 0; k < 8; ++k) o[k] = __builtin_amdgcn_exp2f(z[k]);
; #pragma unroll
;                 for (int k = 0; k < 8; ++k) o[k] += 1.f;
; #pragma unroll
;                 for (int k = 0; k < 8; ++k) o[k] = __builtin_amdgcn_rcpf(o[k]);
; #pragma unroll
;                 for (int k = 0; k < 8; ++k) z[k] *= acc[ai][0][m][k >> 2][k & 3];
; #pragma unroll
;                 for (int k = 0; k < 8; ++k) o[k] *= z[k];
;                 u32x4 w; w.x = cvt_pk_bf16(o[0], o[1]); w.y = cvt_pk_bf16(o[2], o[3]); w.z = cvt_pk_bf16(o[4], o[5]); w.w = cvt_pk_bf16(o[6], o[7]);
;                 *(u32x4*)(act + (size_t)row * FF + col) = w;
	v_mov_b32_dpp v204, v82 row_shr:1 row_mask:0xf bank_mask:0xf
	v_mov_b32_dpp v205, v83 row_shr:1 row_mask:0xf bank_mask:0xf
	v_pk_fma_f32 v[136:137], v[142:143], v[136:137], v[144:145]
	v_pk_mul_f32 v[148:149], v[148:149], s[4:5] op_sel_hi:[1,0]
	v_pk_fma_f32 v[136:137], v[146:147], v[204:205], v[136:137]
	v_exp_f32_e32 v125, v134
	v_pk_mul_f32 v[138:139], v[70:71], v[138:139]
	v_pk_fma_f32 v[136:137], v[82:83], v[148:149], v[136:137]
	v_pk_mul_f32 v[94:95], v[138:139], v[94:95]
	v_add_f32_e32 v139, 1.0, v140
	v_exp_f32_e32 v140, v136
	v_exp_f32_e32 v141, v137
	v_add_f32_e32 v125, 1.0, v125
	v_rcp_f32_e32 v138, v125
	v_rcp_f32_e32 v139, v139
	v_add_f32_e32 v125, 1.0, v140
	v_add_f32_e32 v141, 1.0, v141
	v_rcp_f32_e32 v140, v125
	v_rcp_f32_e32 v141, v141
	s_lshl_b32 s4, s52, 8
	v_pk_mul_f32 v[134:135], v[72:73], v[134:135]
	s_add_i32 s4, s4, s28
	v_pk_mul_f32 v[138:139], v[134:135], v[138:139]
	v_pk_mul_f32 v[134:135], v[74:75], v[136:137]
	v_or_b32_e32 v172, s4, v210
	v_pk_mul_f32 v[140:141], v[134:135], v[140:141]
	v_cvt_pk_bf16_f32 v135, v94, v95
	v_mov_b64_e32 v[94:95], s[92:93]
	s_movk_i32 s6, 0x2c00
	v_cvt_pk_bf16_f32 v134, v88, v89
	v_cvt_pk_bf16_f32 v136, v138, v139
	v_mad_i64_i32 v[138:139], s[4:5], v172, s6, v[94:95]
	v_lshlrev_b64 v[88:89], 1, v[188:189]
	v_cvt_pk_bf16_f32 v137, v140, v141
	v_lshl_add_u64 v[138:139], v[138:139], 0, v[88:89]
	global_store_dwordx4 v[138:139], v[134:137], off
	v_mov_b32_dpp v140, v78 row_ror:2 row_mask:0xf bank_mask:0xf bound_ctrl:1
	v_mov_b32_dpp v141, v79 row_ror:2 row_mask:0xf bank_mask:0xf bound_ctrl:1
	v_mov_b32_dpp v136, v76 row_ror:2 row_mask:0xf bank_mask:0xf bound_ctrl:1
	v_mov_b32_dpp v137, v77 row_ror:2 row_mask:0xf bank_mask:0xf bound_ctrl:1
	v_mov_b32_dpp v134, v76 row_ror:1 row_mask:0xf bank_mask:0xf bound_ctrl:1
	v_mov_b32_dpp v136, v122 row_shr:2 row_mask:0xf bank_mask:0xf
	v_mov_b32_dpp v135, v77 row_ror:1 row_mask:0xf bank_mask:0xf bound_ctrl:1
	v_mov_b32_dpp v137, v123 row_shr:2 row_mask:0xf bank_mask:0xf
	v_mov_b32_dpp v134, v122 row_shr:1 row_mask:0xf bank_mask:0xf
	v_mov_b32_dpp v135, v123 row_shr:1 row_mask:0xf bank_mask:0xf
	v_pk_fma_f32 v[136:137], v[170:171], v[136:137], v[194:195]
	v_mov_b32_dpp v138, v78 row_ror:1 row_mask:0xf bank_mask:0xf bound_ctrl:1
	v_pk_fma_f32 v[134:135], v[190:191], v[134:135], v[136:137]
	v_mov_b32_dpp v140, v116 row_shr:2 row_mask:0xf bank_mask:0xf
	v_pk_fma_f32 v[134:135], v[122:123], v[192:193], v[134:135]
	v_mov_b32_dpp v139, v79 row_ror:1 row_mask:0xf bank_mask:0xf bound_ctrl:1
	v_exp_f32_e32 v125, v134
	v_exp_f32_e32 v136, v135
	v_mov_b32_dpp v141, v117 row_shr:2 row_mask:0xf bank_mask:0xf
	v_mov_b32_dpp v138, v116 row_shr:1 row_mask:0xf bank_mask:0xf
	v_mov_b32_dpp v139, v117 row_shr:1 row_mask:0xf bank_mask:0xf
	v_pk_fma_f32 v[140:141], v[166:167], v[140:141], v[152:153]
	v_add_f32_e32 v125, 1.0, v125
	v_pk_fma_f32 v[138:139], v[164:165], v[138:139], v[140:141]
	v_add_f32_e32 v137, 1.0, v136
	v_pk_fma_f32 v[138:139], v[116:117], v[156:157], v[138:139]
	v_rcp_f32_e32 v136, v125
	v_rcp_f32_e32 v137, v137
	v_exp_f32_e32 v125, v138
	v_exp_f32_e32 v140, v139
	v_mov_b32_dpp v204, v80 row_ror:2 row_mask:0xf bank_mask:0xf bound_ctrl:1
	v_mov_b32_dpp v205, v81 row_ror:2 row_mask:0xf bank_mask:0xf bound_ctrl:1
	v_pk_mul_f32 v[134:135], v[168:169], v[134:135]
	v_mov_b32_dpp v202, v80 row_ror:1 row_mask:0xf bank_mask:0xf bound_ctrl:1
	v_mov_b32_dpp v204, v98 row_shr:2 row_mask:0xf bank_mask:0xf
	v_mov_b32_dpp v203, v81 row_ror:1 row_mask:0xf bank_mask:0xf bound_ctrl:1
	v_mov_b32_dpp v205, v99 row_shr:2 row_mask:0xf bank_mask:0xf
	v_pk_mul_f32 v[134:135], v[134:135], v[136:137]
	v_add_f32_e32 v125, 1.0, v125
	v_add_f32_e32 v137, 1.0, v140
	v_mov_b32_dpp v202, v98 row_shr:1 row_mask:0xf bank_mask:0xf
	v_mov_b32_dpp v203, v99 row_shr:1 row_mask:0xf bank_mask:0xf
	v_rcp_f32_e32 v136, v125
	v_rcp_f32_e32 v137, v137
	v_pk_fma_f32 v[140:141], v[162:163], v[204:205], v[150:151]
	v_mov_b32_e32 v209, v208
	v_pk_fma_f32 v[140:141], v[154:155], v[202:203], v[140:141]
	v_mov_b32_dpp v212, v82 row_ror:2 row_mask:0xf bank_mask:0xf bound_ctrl:1
	v_mov_b32_dpp v213, v83 row_ror:2 row_mask:0xf bank_mask:0xf bound_ctrl:1
	v_pk_fma_f32 v[140:141], v[98:99], v[158:159], v[140:141]
	v_pk_mul_f32 v[104:105], v[104:105], v[208:209]
	v_pk_mul_f32 v[100:101], v[100:101], v[208:209]
	v_mov_b32_dpp v208, v82 row_ror:1 row_mask:0xf bank_mask:0xf bound_ctrl:1
	v_mov_b32_dpp v212, v96 row_shr:2 row_mask:0xf bank_mask:0xf
	v_mov_b32_dpp v209, v83 row_ror:1 row_mask:0xf bank_mask:0xf bound_ctrl:1
	v_mov_b32_dpp v213, v97 row_shr:2 row_mask:0xf bank_mask:0xf
	v_exp_f32_e32 v168, v141
	v_pk_mul_f32 v[138:139], v[160:161], v[138:139]
	v_mov_b32_dpp v208, v96 row_shr:1 row_mask:0xf bank_mask:0xf
	v_mov_b32_dpp v209, v97 row_shr:1 row_mask:0xf bank_mask:0xf
	v_pk_mul_f32 v[136:137], v[138:139], v[136:137]
	v_pk_fma_f32 v[138:139], v[142:143], v[212:213], v[144:145]
	v_exp_f32_e32 v125, v140
	v_pk_fma_f32 v[138:139], v[146:147], v[208:209], v[138:139]
	v_add_f32_e32 v161, 1.0, v168
	v_pk_fma_f32 v[138:139], v[96:97], v[148:149], v[138:139]
	v_add_f32_e32 v125, 1.0, v125
	v_exp_f32_e32 v168, v138
	v_exp_f32_e32 v169, v139
	v_rcp_f32_e32 v160, v125
	v_rcp_f32_e32 v161, v161
	v_add_f32_e32 v125, 1.0, v168
	v_add_f32_e32 v169, 1.0, v169
	v_rcp_f32_e32 v168, v125
	v_rcp_f32_e32 v169, v169
	v_pk_mul_f32 v[118:119], v[118:119], v[206:207] op_sel_hi:[1,0]
	v_pk_mul_f32 v[120:121], v[120:121], v[140:141]
	v_pk_mul_f32 v[118:119], v[118:119], v[138:139]
	v_or_b32_e32 v125, 16, v172
	v_pk_mul_f32 v[120:121], v[120:121], v[160:161]
	v_pk_mul_f32 v[138:139], v[118:119], v[168:169]
; __device__ __forceinline__ unsigned cvt_pk_bf16(float lo, float hi) { const f32x2 v = {lo, hi}; const bf16v2_ r = __builtin_convertvector(v, bf16v2_); return __builtin_bit_cast(unsigned, r); }
;     __device__ __forceinline__ void operator()(f32x4 (&acc)[2][2][4][2], const Unit& u, int wr, int wc, int ui, int) const {
;     ...
;             for (int m = 0; m < 4; ++m) {
;                 const int row = u.pm * BM + ai * HALF + wr * 64 + m * 16 + fr;
;                 float o[8], z[8], g1[8], g2[8];
; #pragma unroll
;                 for (int k = 0; k < 8; ++k) { const int n = k >> 2, e = k & 3;
;                     const float gc = acc[ai][1][m][n][e], gp = (m == 0) ? hal[n][e] : acc[ai][1][m - 1][n][e];
;                     const int gci = __builtin_bit_cast(int, gc), gpi = __builtin_bit_cast(int, gp);
;                     const int r1 = __builtin_amdgcn_update_dpp(0, gpi, 0x121, 0xf, 0xf, true), r2 = __builtin_amdgcn_update_dpp(0, gpi, 0x122, 0xf, 0xf, true);
;                     g1[k] = __builtin_bit_cast(float, __builtin_amdgcn_update_dpp(r1, gci, 0x111, 0xf, 0xf, false));
;                     g2[k] = __builtin_bit_cast(float, __builtin_amdgcn_update_dpp(r2, gci, 0x112, 0xf, 0xf, false)); }
; #pragma unroll
;                 for (int k = 0; k < 8; ++k) z[k] = w0[k] * g2[k] + bb[k];
; #pragma unroll
;                 for (int k = 0; k < 8; ++k) z[k] += w1[k] * g1[k];
; #pragma unroll
;                 for (int k = 0; k < 8; ++k) z[k] += w2[k] * acc[ai][1][m][k >> 2][k & 3];
; #pragma unroll
;                 for (int k = 0; k < 8; ++k) o[k] = __builtin_amdgcn_exp2f(z[k]);
; #pragma unroll
;                 for (int k = 0; k < 8; ++k) o[k] += 1.f;
; #pragma unroll
;                 for (int k = 0; k < 8; ++k) o[k] = __builtin_amdgcn_rcpf(o[k]);
; #pragma unroll
;                 for (int k = 0; k < 8; ++k) z[k] *= acc[ai][0][m][k >> 2][k & 3];
; #pragma unroll
;                 for (int k = 0; k < 8; ++k) o[k] *= z[k];
;                 u32x4 w; w.x = cvt_pk_bf16(o[0], o[1]); w.y = cvt_pk_bf16(o[2], o[3]); w.z = cvt_pk_bf16(o[4], o[5]); w.w = cvt_pk_bf16(o[6], o[7]);
;                 *(u32x4*)(act + (size_t)row * FF + col) = w;
	v_cvt_pk_bf16_f32 v118, v134, v135
	v_mad_i64_i32 v[134:135], s[4:5], v125, s6, v[94:95]
	v_cvt_pk_bf16_f32 v119, v136, v137
	v_cvt_pk_bf16_f32 v120, v120, v121
	v_cvt_pk_bf16_f32 v121, v138, v139
	v_lshl_add_u64 v[134:135], v[134:135], 0, v[88:89]
	global_store_dwordx4 v[134:135], v[118:121], off
	v_mov_b32_dpp v136, v96 row_ror:1 row_mask:0xf bank_mask:0xf bound_ctrl:1
	v_mov_b32_dpp v134, v98 row_ror:1 row_mask:0xf bank_mask:0xf bound_ctrl:1
	v_mov_b32_dpp v118, v122 row_ror:1 row_mask:0xf bank_mask:0xf bound_ctrl:1
	v_mov_b32_dpp v120, v122 row_ror:2 row_mask:0xf bank_mask:0xf bound_ctrl:1
	v_mov_b32_dpp v119, v123 row_ror:1 row_mask:0xf bank_mask:0xf bound_ctrl:1
	v_mov_b32_dpp v121, v123 row_ror:2 row_mask:0xf bank_mask:0xf bound_ctrl:1
	v_mov_b32_dpp v122, v116 row_ror:1 row_mask:0xf bank_mask:0xf bound_ctrl:1
	v_mov_b32_dpp v116, v116 row_ror:2 row_mask:0xf bank_mask:0xf bound_ctrl:1
	v_mov_b32_dpp v123, v117 row_ror:1 row_mask:0xf bank_mask:0xf bound_ctrl:1
	v_mov_b32_dpp v117, v117 row_ror:2 row_mask:0xf bank_mask:0xf bound_ctrl:1
	v_mov_b32_dpp v120, v92 row_shr:2 row_mask:0xf bank_mask:0xf
	v_mov_b32_dpp v121, v93 row_shr:2 row_mask:0xf bank_mask:0xf
	v_mov_b32_dpp v116, v90 row_shr:2 row_mask:0xf bank_mask:0xf
	v_mov_b32_dpp v117, v91 row_shr:2 row_mask:0xf bank_mask:0xf
	v_mov_b32_dpp v118, v92 row_shr:1 row_mask:0xf bank_mask:0xf
	v_mov_b32_dpp v119, v93 row_shr:1 row_mask:0xf bank_mask:0xf
	v_mov_b32_dpp v122, v90 row_shr:1 row_mask:0xf bank_mask:0xf
	v_mov_b32_dpp v123, v91 row_shr:1 row_mask:0xf bank_mask:0xf
	v_pk_fma_f32 v[120:121], v[170:171], v[120:121], v[194:195]
	v_pk_fma_f32 v[116:117], v[166:167], v[116:117], v[152:153]
	v_pk_fma_f32 v[118:119], v[190:191], v[118:119], v[120:121]
	v_pk_fma_f32 v[116:117], v[164:165], v[122:123], v[116:117]
	v_pk_fma_f32 v[118:119], v[92:93], v[192:193], v[118:119]
	v_pk_fma_f32 v[116:117], v[90:91], v[156:157], v[116:117]
	v_exp_f32_e32 v120, v118
	v_exp_f32_e32 v121, v119
	v_exp_f32_e32 v122, v116
	v_exp_f32_e32 v123, v117
	v_mov_b32_dpp v98, v98 row_ror:2 row_mask:0xf bank_mask:0xf bound_ctrl:1
	v_mov_b32_dpp v135, v99 row_ror:1 row_mask:0xf bank_mask:0xf bound_ctrl:1
	v_mov_b32_dpp v99, v99 row_ror:2 row_mask:0xf bank_mask:0xf bound_ctrl:1
	v_mov_b32_dpp v96, v96 row_ror:2 row_mask:0xf bank_mask:0xf bound_ctrl:1
	v_mov_b32_dpp v137, v97 row_ror:1 row_mask:0xf bank_mask:0xf bound_ctrl:1
	v_mov_b32_dpp v97, v97 row_ror:2 row_mask:0xf bank_mask:0xf bound_ctrl:1
	v_add_f32_e32 v120, 1.0, v120
	v_add_f32_e32 v121, 1.0, v121
	v_pk_mul_f32 v[112:113], v[112:113], v[118:119]
	v_add_f32_e32 v118, 1.0, v122
	v_add_f32_e32 v119, 1.0, v123
	v_mov_b32_dpp v98, v84 row_shr:2 row_mask:0xf bank_mask:0xf
	v_mov_b32_dpp v99, v85 row_shr:2 row_mask:0xf bank_mask:0xf
	v_mov_b32_dpp v96, v86 row_shr:2 row_mask:0xf bank_mask:0xf
	v_mov_b32_dpp v97, v87 row_shr:2 row_mask:0xf bank_mask:0xf
	v_rcp_f32_e32 v120, v120
	v_rcp_f32_e32 v121, v121
	v_rcp_f32_e32 v118, v118
	v_rcp_f32_e32 v119, v119
	v_mov_b32_dpp v134, v84 row_shr:1 row_mask:0xf bank_mask:0xf
	v_mov_b32_dpp v135, v85 row_shr:1 row_mask:0xf bank_mask:0xf
	v_mov_b32_dpp v136, v86 row_shr:1 row_mask:0xf bank_mask:0xf
	v_mov_b32_dpp v137, v87 row_shr:1 row_mask:0xf bank_mask:0xf
	v_pk_fma_f32 v[98:99], v[162:163], v[98:99], v[150:151]
	v_pk_fma_f32 v[96:97], v[142:143], v[96:97], v[144:145]
	v_pk_fma_f32 v[98:99], v[154:155], v[134:135], v[98:99]
	v_pk_fma_f32 v[96:97], v[146:147], v[136:137], v[96:97]
	v_pk_fma_f32 v[98:99], v[84:85], v[158:159], v[98:99]
	v_pk_mul_f32 v[114:115], v[114:115], v[116:117]
	v_pk_fma_f32 v[96:97], v[86:87], v[148:149], v[96:97]
	v_pk_mul_f32 v[112:113], v[112:113], v[120:121]
	v_exp_f32_e32 v120, v98
	v_exp_f32_e32 v121, v99
	v_pk_mul_f32 v[114:115], v[114:115], v[118:119]
	v_exp_f32_e32 v118, v96
	v_exp_f32_e32 v119, v97
	v_add_f32_e32 v116, 1.0, v120
	v_add_f32_e32 v117, 1.0, v121
	v_add_f32_e32 v118, 1.0, v118
	v_add_f32_e32 v119, 1.0, v119
	v_rcp_f32_e32 v116, v116
	v_rcp_f32_e32 v117, v117
	v_rcp_f32_e32 v118, v118
	v_rcp_f32_e32 v119, v119
	v_pk_mul_f32 v[98:99], v[108:109], v[98:99]
	v_pk_mul_f32 v[96:97], v[110:111], v[96:97]
	v_pk_mul_f32 v[98:99], v[98:99], v[116:117]
	v_pk_mul_f32 v[108:109], v[96:97], v[118:119]
	v_or_b32_e32 v110, 32, v172
	v_cvt_pk_bf16_f32 v98, v98, v99
	v_cvt_pk_bf16_f32 v99, v108, v109
	v_mad_i64_i32 v[108:109], s[4:5], v110, s6, v[94:95]
	v_cvt_pk_bf16_f32 v96, v112, v113
	v_cvt_pk_bf16_f32 v97, v114, v115
	v_lshl_add_u64 v[108:109], v[108:109], 0, v[88:89]
	global_store_dwordx4 v[108:109], v[96:99], off
;     __device__ __forceinline__ void operator()(f32x4 (&acc)[2][2][4][2], const Unit& u, int wr, int wc, int ui, int) const {
;     ...
;             f32x4 hal[2] = {(f32x4){0.f, 0.f, 0.f, 0.f}, (f32x4){0.f, 0.f, 0.f, 0.f}};
;             if (!(ai == 0 && wr == 0) && fr >= 14) {
;                 const int sai = (wr == 1) ? ai : 0, swr = (wr == 1) ? 0 : 1;
;                 const LAS f32x4* s = (const LAS f32x4*)(hl + ((((sai * 2 + swr) * 4 + wc) * 8 + fq * 2 + (fr - 14)) * 32));
;                 hal[0] = s[0]; hal[1] = s[1];
;             }
;     ...
;             for (int m = 0; m < 4; ++m) {
;                 const int row = u.pm * BM + ai * HALF + wr * 64 + m * 16 + fr;
;                 float o[8], z[8], g1[8], g2[8];
; #pragma unroll
;                 for (int k = 0; k < 8; ++k) { const int n = k >> 2, e = k & 3;
;                     const float gc = acc[ai][1][m][n][e], gp = (m == 0) ? hal[n][e] : acc[ai][1][m - 1][n][e];
;                     const int gci = __builtin_bit_cast(int, gc), gpi = __builtin_bit_cast(int, gp);
;                     const int r1 = __builtin_amdgcn_update_dpp(0, gpi, 0x121, 0xf, 0xf, true), r2 = __builtin_amdgcn_update_dpp(0, gpi, 0x122, 0xf, 0xf, true);
;                     g1[k] = __builtin_bit_cast(float, __builtin_amdgcn_update_dpp(r1, gci, 0x111, 0xf, 0xf, false));
;                     g2[k] = __builtin_bit_cast(float, __builtin_amdgcn_update_dpp(r2, gci, 0x112, 0xf, 0xf, false)); }
; #pragma unroll
;                 for (int k = 0; k < 8; ++k) z[k] = w0[k] * g2[k] + bb[k];
; #pragma unroll
;                 for (int k = 0; k < 8; ++k) z[k] += w1[k] * g1[k];
; #pragma unroll
;                 for (int k = 0; k < 8; ++k) z[k] += w2[k] * acc[ai][1][m][k >> 2][k & 3];
; #pragma unroll
;                 for (int k = 0; k < 8; ++k) o[k] = __builtin_amdgcn_exp2f(z[k]);
; #pragma unroll
;                 for (int k = 0; k < 8; ++k) o[k] += 1.f;
; #pragma unroll
;                 for (int k = 0; k < 8; ++k) o[k] = __builtin_amdgcn_rcpf(o[k]);
; #pragma unroll
;                 for (int k = 0; k < 8; ++k) z[k] *= acc[ai][0][m][k >> 2][k & 3];
; #pragma unroll
;                 for (int k = 0; k < 8; ++k) o[k] *= z[k];
;                 u32x4 w; w.x = cvt_pk_bf16(o[0], o[1]); w.y = cvt_pk_bf16(o[2], o[3]); w.z = cvt_pk_bf16(o[4], o[5]); w.w = cvt_pk_bf16(o[6], o[7]);
;                 *(u32x4*)(act + (size_t)row * FF + col) = w;
	v_mov_b32_dpp v110, v86 row_ror:1 row_mask:0xf bank_mask:0xf bound_ctrl:1
	v_mov_b32_dpp v108, v84 row_ror:1 row_mask:0xf bank_mask:0xf bound_ctrl:1
	v_mov_b32_dpp v96, v92 row_ror:1 row_mask:0xf bank_mask:0xf bound_ctrl:1
	v_mov_b32_dpp v92, v92 row_ror:2 row_mask:0xf bank_mask:0xf bound_ctrl:1
	v_mov_b32_dpp v97, v93 row_ror:1 row_mask:0xf bank_mask:0xf bound_ctrl:1
	v_mov_b32_dpp v93, v93 row_ror:2 row_mask:0xf bank_mask:0xf bound_ctrl:1
	v_mov_b32_dpp v92, v130 row_shr:2 row_mask:0xf bank_mask:0xf
	v_mov_b32_dpp v96, v130 row_shr:1 row_mask:0xf bank_mask:0xf
	v_mov_b32_dpp v93, v131 row_shr:2 row_mask:0xf bank_mask:0xf
	v_mov_b32_dpp v97, v131 row_shr:1 row_mask:0xf bank_mask:0xf
	v_pk_fma_f32 v[92:93], v[170:171], v[92:93], v[194:195]
	v_mov_b32_dpp v98, v90 row_ror:1 row_mask:0xf bank_mask:0xf bound_ctrl:1
	v_pk_fma_f32 v[92:93], v[190:191], v[96:97], v[92:93]
	v_mov_b32_dpp v90, v90 row_ror:2 row_mask:0xf bank_mask:0xf bound_ctrl:1
	v_pk_fma_f32 v[92:93], v[130:131], v[192:193], v[92:93]
	v_mov_b32_dpp v99, v91 row_ror:1 row_mask:0xf bank_mask:0xf bound_ctrl:1
	v_mov_b32_dpp v91, v91 row_ror:2 row_mask:0xf bank_mask:0xf bound_ctrl:1
	v_exp_f32_e32 v96, v92
	v_exp_f32_e32 v97, v93
	v_mov_b32_dpp v90, v132 row_shr:2 row_mask:0xf bank_mask:0xf
	v_mov_b32_dpp v91, v133 row_shr:2 row_mask:0xf bank_mask:0xf
	v_mov_b32_dpp v98, v132 row_shr:1 row_mask:0xf bank_mask:0xf
	v_mov_b32_dpp v99, v133 row_shr:1 row_mask:0xf bank_mask:0xf
	v_pk_fma_f32 v[90:91], v[166:167], v[90:91], v[152:153]
	v_add_f32_e32 v96, 1.0, v96
	v_pk_fma_f32 v[90:91], v[164:165], v[98:99], v[90:91]
	v_add_f32_e32 v97, 1.0, v97
	v_pk_fma_f32 v[90:91], v[132:133], v[156:157], v[90:91]
	v_mov_b32_dpp v84, v84 row_ror:2 row_mask:0xf bank_mask:0xf bound_ctrl:1
	v_mov_b32_dpp v109, v85 row_ror:1 row_mask:0xf bank_mask:0xf bound_ctrl:1
	v_mov_b32_dpp v85, v85 row_ror:2 row_mask:0xf bank_mask:0xf bound_ctrl:1
	v_rcp_f32_e32 v96, v96
	v_rcp_f32_e32 v97, v97
	v_exp_f32_e32 v98, v90
	v_exp_f32_e32 v99, v91
	v_mov_b32_dpp v84, v126 row_shr:2 row_mask:0xf bank_mask:0xf
	v_mov_b32_dpp v85, v127 row_shr:2 row_mask:0xf bank_mask:0xf
	v_mov_b32_dpp v108, v126 row_shr:1 row_mask:0xf bank_mask:0xf
	v_mov_b32_dpp v109, v127 row_shr:1 row_mask:0xf bank_mask:0xf
	v_pk_fma_f32 v[84:85], v[162:163], v[84:85], v[150:151]
	v_pk_mul_f32 v[92:93], v[104:105], v[92:93]
	v_pk_fma_f32 v[84:85], v[154:155], v[108:109], v[84:85]
	v_mov_b32_dpp v86, v86 row_ror:2 row_mask:0xf bank_mask:0xf bound_ctrl:1
	v_mov_b32_dpp v111, v87 row_ror:1 row_mask:0xf bank_mask:0xf bound_ctrl:1
	v_mov_b32_dpp v87, v87 row_ror:2 row_mask:0xf bank_mask:0xf bound_ctrl:1
	v_pk_mul_f32 v[92:93], v[92:93], v[96:97]
	v_add_f32_e32 v96, 1.0, v98
	v_add_f32_e32 v97, 1.0, v99
	v_pk_fma_f32 v[84:85], v[126:127], v[158:159], v[84:85]
	v_mov_b32_dpp v86, v128 row_shr:2 row_mask:0xf bank_mask:0xf
	v_mov_b32_dpp v87, v129 row_shr:2 row_mask:0xf bank_mask:0xf
	v_rcp_f32_e32 v96, v96
	v_rcp_f32_e32 v97, v97
	v_exp_f32_e32 v98, v84
	v_exp_f32_e32 v99, v85
	v_mov_b32_dpp v110, v128 row_shr:1 row_mask:0xf bank_mask:0xf
	v_mov_b32_dpp v111, v129 row_shr:1 row_mask:0xf bank_mask:0xf
	v_pk_fma_f32 v[86:87], v[142:143], v[86:87], v[144:145]
	v_pk_mul_f32 v[90:91], v[106:107], v[90:91]
	v_pk_fma_f32 v[86:87], v[146:147], v[110:111], v[86:87]
	v_pk_mul_f32 v[90:91], v[90:91], v[96:97]
	v_pk_fma_f32 v[86:87], v[128:129], v[148:149], v[86:87]
	v_add_f32_e32 v96, 1.0, v98
	v_add_f32_e32 v97, 1.0, v99
	v_exp_f32_e32 v98, v86
	v_exp_f32_e32 v99, v87
	v_rcp_f32_e32 v96, v96
	v_rcp_f32_e32 v97, v97
	v_add_f32_e32 v98, 1.0, v98
	v_add_f32_e32 v99, 1.0, v99
	v_rcp_f32_e32 v98, v98
	v_rcp_f32_e32 v99, v99
	v_pk_mul_f32 v[84:85], v[100:101], v[84:85]
	v_or_b32_e32 v100, 48, v172
	v_pk_mul_f32 v[96:97], v[84:85], v[96:97]
	v_pk_mul_f32 v[84:85], v[102:103], v[86:87]
	v_cvt_pk_bf16_f32 v86, v96, v97
	v_pk_mul_f32 v[98:99], v[84:85], v[98:99]
	v_cvt_pk_bf16_f32 v85, v90, v91
	v_mad_i64_i32 v[90:91], s[4:5], v100, s6, v[94:95]
	v_cvt_pk_bf16_f32 v84, v92, v93
	v_cvt_pk_bf16_f32 v87, v98, v99
	v_lshl_add_u64 v[90:91], v[90:91], 0, v[88:89]
	global_store_dwordx4 v[90:91], v[84:87], off
	v_mov_b32_e32 v125, 0
	v_mov_b32_e32 v126, 0
	v_mov_b32_e32 v127, 0
	v_mov_b32_e32 v84, 0
	v_mov_b32_e32 v85, 0
	v_mov_b32_e32 v86, 0
	v_mov_b32_e32 v87, 0
	s_and_saveexec_b64 s[4:5], vcc
	s_mov_b32 s72, s16
	s_mov_b32 s73, s17
	s_cbranch_execz .LBB0_1533
	v_add3_u32 v84, s64, v197, v199
	v_add_u32_e32 v90, 0xfffffe50, v84
	v_add_u32_e32 v84, 0xfffffe40, v84
	ds_read_b128 v[84:87], v84
	ds_read_b128 v[124:127], v90
